# v29: split barrier at up-proj->attention (arrive after up-proj, wait before first MLA/FoX unit; stick-breaking units first in the queue)
# speedup vs baseline: 1.0507x; 1.0090x over previous
; #define LAS __attribute__((address_space(3)))
; __device__ __forceinline__ int opaque_tid(int wv) { unsigned z = 0u; asm volatile("" : "+v"(z)); return (wv << 6) | (int)__builtin_amdgcn_mbcnt_hi(~0u, __builtin_amdgcn_mbcnt_lo(~0u, z)); }
; __device__ __forceinline__ unsigned xb_add(unsigned* p, unsigned v) { return __hip_atomic_fetch_add(p, v, __ATOMIC_RELAXED, __HIP_MEMORY_SCOPE_AGENT); }
; __device__ __forceinline__ unsigned xb_xcc_id() { return (unsigned)__builtin_amdgcn_s_getreg((3 << 11) | 20) & 0xFu; }
; __global__ void __launch_bounds__(512) fwd_megakernel(Args A) {
;     extern __shared__ __attribute__((aligned(16))) unsigned char lds_raw[];
;     LAS unsigned char* lds = (LAS unsigned char*)lds_raw;
;     const int G = gridDim.x, bx = blockIdx.x;
;     const int wv = __builtin_amdgcn_readfirstlane((int)threadIdx.x >> 6);
;     unsigned char* ws = A.ws;
;     const int lo = A.ph_lo, hi = A.ph_hi;
;     ...
;     cg::grid_group grid = cg::this_grid();
;     unsigned* xbar = (unsigned*)(ws + WS_CTL) + 1024;
;     volatile LAS unsigned* xst = (volatile LAS unsigned*)(lds + MISC_OFF + 64);
;     { const int t0_ = opaque_tid(wv); if (t0_ == 0) { xst[0] = 0u; xst[1] = 0u; (void)xb_add(&xbar[XB_XCNT(xb_xcc_id())], 1u); } }
.LBB0_181:
.LBB0_182:
	v_writelane_b32 v255, 0, 11
	s_mov_b64 s[2:3], exec
	s_mov_b64 exec, 1
	s_and_b32 s4, s86, 7
	s_lshl_b32 s4, s4, 8
	s_add_u32 s4, s4, 0x6000
	s_add_u32 s4, s60, s4
	s_addc_u32 s5, s61, 0
	v_mov_b32_e32 v2, 0
	global_load_dword v3, v2, s[4:5] sc1
	s_waitcnt vmcnt(0)
	v_readfirstlane_b32 s6, v3
	s_mov_b64 exec, s[2:3]
	s_bcnt1_i32_b32 s6, s6
	v_readlane_b32 s7, v251, 2
	s_mov_b32 s100, 0
	s_mov_b32 s101, 0
	s_cmpk_lg_i32 s7, 0x100
	s_cbranch_scc1 .Lmode_done
	s_mov_b32 s100, 1
	s_cmp_lg_u32 s6, 1
	s_cbranch_scc1 .Lmode_done
	s_mov_b32 s100, 2

; #define LAS __attribute__((address_space(3)))
; __device__ __forceinline__ unsigned xb_ld(unsigned* p)              { return __hip_atomic_load(p, __ATOMIC_RELAXED, __HIP_MEMORY_SCOPE_AGENT); }
; __device__ __forceinline__ unsigned xb_add(unsigned* p, unsigned v) { return __hip_atomic_fetch_add(p, v, __ATOMIC_RELAXED, __HIP_MEMORY_SCOPE_AGENT); }
; __device__ __forceinline__ unsigned xb_xcc_id() { return (unsigned)__builtin_amdgcn_s_getreg((3 << 11) | 20) & 0xFu; }
; #define XB_SPIN(cond, bar) do { unsigned _sp = 0; while (cond) { __builtin_amdgcn_s_sleep(1); \
;     if ((++_sp & 255u) == 0u) { if (xb_ld(&(bar)[XB_TMO])) break; if (_sp > XB_SPIN_CAP) { atomicAdd(&(bar)[XB_TMO], 1u); break; } } } } while (0)
; #define SEAM(k) do { } while (0)
; #define SEAM(k) do { if (lo <= (k) && (k) + 1 < hi) { if (hi > 1000) grid.sync(); else xcd_barrier(xbar, xst, opaque_tid(wv) == 0); } } while (0)
; __device__ __forceinline__ void xcd_barrier(unsigned* bar, volatile LAS unsigned* st, bool is0) {
;     asm volatile("s_waitcnt vmcnt(0)" ::: "memory");
;     __syncthreads();
;     if (is0) {
;         __builtin_amdgcn_s_waitcnt(0);
;         const unsigned x = xb_xcc_id();
;         unsigned nloc = st[0], nx = st[1];
;         if (nloc == 0u) { xcd_barrier_complete(bar, x, nloc, nx); st[0] = nloc; st[1] = nx; }
;         const unsigned old = xb_add(&bar[XB_XSUB(x)], 1u);
;         const unsigned gen = old / nloc;
;         if (old + 1u == (gen + 1u) * nloc) {
;             __builtin_amdgcn_fence(__ATOMIC_RELEASE, "agent");
;             asm volatile("s_waitcnt vmcnt(0)" ::: "memory");
;             const unsigned og = xb_add(&bar[XB_TOP], 1u);
;             const unsigned tg = og / nx;
;             if (og + 1u == (tg + 1u) * nx) xb_add(&bar[XB_TOPGEN], 1u);
;             else XB_SPIN(xb_ld(&bar[XB_TOPGEN]) == tg, bar);
;             __builtin_amdgcn_fence(__ATOMIC_ACQUIRE, "agent");
;             xb_add(&bar[XB_XGEN(x)], 1u);
;             asm volatile("s_waitcnt vmcnt(0)" ::: "memory");
;         } else {
;             XB_SPIN(xb_ld(&bar[XB_XGEN(x)]) == gen, bar);
;             __builtin_amdgcn_fence(__ATOMIC_ACQUIRE, "agent");
;             asm volatile("s_waitcnt vmcnt(0)" ::: "memory");
;         }
;     }
;     __syncthreads();
; }
; __global__ void __launch_bounds__(512) fwd_megakernel(Args A) {
;     ...
;             SEAM(P + 2);
.LBB0_449:
	v_readlane_b32 s0, v254, 45
	v_readlane_b32 s4, v251, 41
	s_or_b32 s0, s0, 4
	v_readlane_b32 s11, v251, 48
	s_cmp_ge_i32 s0, s11
	v_readlane_b32 s1, v254, 46
	v_readlane_b32 s5, v251, 42
	v_readlane_b32 s6, v251, 43
	v_readlane_b32 s7, v251, 44
	v_readlane_b32 s8, v251, 45
	v_readlane_b32 s9, v251, 46
	v_readlane_b32 s10, v251, 47
	s_cbranch_scc1 .LBB0_516
	v_readlane_b32 s4, v252, 13
	v_readlane_b32 s5, v252, 14
	s_mov_b64 s[2:3], -1
	s_and_b64 vcc, exec, s[4:5]
	s_cbranch_vccz .LBB0_504
	s_cmp_eq_u32 s100, 0
	s_cbranch_scc1 .Lsa_orig
	s_waitcnt vmcnt(0) lgkmcnt(0)
	s_barrier
	s_cmp_lg_u32 s94, 0
	s_cbranch_scc1 .Lsa_join
	s_mov_b64 exec, 1
	v_readlane_b32 s8, v251, 45
	v_readlane_b32 s9, v251, 46
	v_readlane_b32 s6, v251, 50
	v_mov_b32_e32 v4, 1
	v_mov_b32_e32 v8, 0
	s_and_b32 s6, s6, 7
	s_lshl_b32 s6, s6, 6
	s_add_u32 s6, s6, 0x6800
	s_add_u32 s10, s8, s6
	s_addc_u32 s11, s9, 0
	s_add_u32 s8, s8, 0x6c00
	s_addc_u32 s9, s9, 0
	s_add_u32 s12, s80, 1
	s_lshl_b32 s13, s12, 5
	s_cmp_eq_u32 s100, 2
	s_cbranch_scc1 .Lsa_arr
	buffer_wbl2 sc1
	s_waitcnt vmcnt(0)
.Lsa_arr:
	global_atomic_add v6, v8, v4, s[10:11] sc0
	s_waitcnt vmcnt(0)
	v_readfirstlane_b32 s15, v6
	s_nop 1
	s_add_u32 s15, s15, 1
	s_cmp_eq_u32 s15, s13
	s_cbranch_scc0 .Lsa_done
	s_cmp_lg_u32 s100, 2
	s_cbranch_scc1 .Lsa_top
	buffer_wbl2 sc1
	s_waitcnt vmcnt(0)
.Lsa_top:
	global_atomic_add v8, v4, s[8:9]

; #define LAS __attribute__((address_space(3)))
; __device__ __forceinline__ unsigned xb_add(unsigned* p, unsigned v) { return __hip_atomic_fetch_add(p, v, __ATOMIC_RELAXED, __HIP_MEMORY_SCOPE_AGENT); }
; __device__ __forceinline__ unsigned xb_xcc_id() { return (unsigned)__builtin_amdgcn_s_getreg((3 << 11) | 20) & 0xFu; }
; __device__ __forceinline__ void xcd_barrier(unsigned* bar, volatile LAS unsigned* st, bool is0) {
;     asm volatile("s_waitcnt vmcnt(0)" ::: "memory");
;     __syncthreads();
;     if (is0) {
;         __builtin_amdgcn_s_waitcnt(0);
;         const unsigned x = xb_xcc_id();
;         unsigned nloc = st[0], nx = st[1];
;         if (nloc == 0u) { xcd_barrier_complete(bar, x, nloc, nx); st[0] = nloc; st[1] = nx; }
;         const unsigned old = xb_add(&bar[XB_XSUB(x)], 1u);
.Lsa_orig:
	v_mov_b32_e32 v0, v1
	s_waitcnt vmcnt(0)
	s_waitcnt vmcnt(0)
	v_mbcnt_lo_u32_b32 v0, -1, v0
	v_mbcnt_hi_u32_b32 v0, -1, v0
	v_or_b32_e32 v0, s94, v0
	v_cmp_eq_u32_e32 vcc, 0, v0
	s_barrier
	s_and_saveexec_b64 s[2:3], vcc
	s_cbranch_execz .LBB0_503
	v_readlane_b32 s4, v254, 35
	s_waitcnt vmcnt(0) expcnt(0) lgkmcnt(0)
	s_getreg_b32 s1, hwreg(HW_REG_XCC_ID, 0, 4)
	v_mov_b32_e32 v0, s4
	ds_read_b32 v3, v0
	v_readlane_b32 s4, v254, 36
	s_and_b32 s1, s1, 15
	s_waitcnt lgkmcnt(0)
	v_cmp_ne_u32_e32 vcc, 0, v3
	v_mov_b32_e32 v0, s4
	ds_read_b32 v2, v0
	s_cbranch_vccnz .LBB0_467
	s_mov_b32 s10, 1
	s_branch .LBB0_455

; #define LAS __attribute__((address_space(3)))
; __device__ __forceinline__ int opaque_tid(int wv) { unsigned z = 0u; asm volatile("" : "+v"(z)); return (wv << 6) | (int)__builtin_amdgcn_mbcnt_hi(~0u, __builtin_amdgcn_mbcnt_lo(~0u, z)); }
; __device__ __forceinline__ unsigned xb_add(unsigned* p, unsigned v) { return __hip_atomic_fetch_add(p, v, __ATOMIC_RELAXED, __HIP_MEMORY_SCOPE_AGENT); }
; __device__ __forceinline__ unsigned xb_xcc_id() { return (unsigned)__builtin_amdgcn_s_getreg((3 << 11) | 20) & 0xFu; }
; __global__ void __launch_bounds__(512) fwd_megakernel(Args A) {
;     ...
;     cg::grid_group grid = cg::this_grid();
;     unsigned* xbar = (unsigned*)(ws + WS_CTL) + 1024;
;     volatile LAS unsigned* xst = (volatile LAS unsigned*)(lds + MISC_OFF + 64);
;     { const int t0_ = opaque_tid(wv); if (t0_ == 0) { xst[0] = 0u; xst[1] = 0u; (void)xb_add(&xbar[XB_XCNT(xb_xcc_id())], 1u); } }
.Lsa_after:
.LBB0_504:
	s_and_b64 vcc, exec, s[2:3]
	s_cbranch_vccz .LBB0_516
	s_waitcnt vmcnt(0)
	s_barrier
	s_mov_b64 s[2:3], exec
	v_readlane_b32 s4, v254, 37
	v_readlane_b32 s5, v254, 38
	s_and_b64 s[4:5], s[2:3], s[4:5]
	s_mov_b64 exec, s[4:5]
	s_cbranch_execz .LBB0_515
	v_readlane_b32 s4, v251, 0
	v_readlane_b32 s5, v251, 1
	buffer_wbl2 sc1
	s_load_dwordx2 s[4:5], s[4:5], 0x58
	s_mov_b64 s[6:7], exec
	v_mbcnt_lo_u32_b32 v2, s6, 0
	v_mbcnt_hi_u32_b32 v2, s7, v2
	v_cmp_eq_u32_e32 vcc, 0, v2
	s_waitcnt lgkmcnt(0)
	global_load_dword v0, v1, s[4:5] offset:40
	s_and_saveexec_b64 s[8:9], vcc
	s_cbranch_execz .LBB0_508
	s_bcnt1_i32_b64 s1, s[6:7]
	v_mov_b32_e32 v3, s1
	global_atomic_add v3, v1, v3, s[4:5] offset:32 sc0

; __device__ __forceinline__ int opaque_tid(int wv) { unsigned z = 0u; asm volatile("" : "+v"(z)); return (wv << 6) | (int)__builtin_amdgcn_mbcnt_hi(~0u, __builtin_amdgcn_mbcnt_lo(~0u, z)); }
; __device__ __forceinline__ int att_code(int grp) {
;     const unsigned long long w = (grp < 12) ? 0xab2c36dc8e794c7ull : 0x820114c82a9d162ull;
;     return (int)((w >> (5 * ((grp < 12) ? grp : grp - 12))) & 31ull);
; }
; __global__ void __launch_bounds__(512) fwd_megakernel(Args A) {
;     ...
;             for (int ui_ = 0;; ++ui_) {
;                 int idx;
;                 if (ATT_DYNQ) {
;                     if (ui_ == 0) idx = bx;
;                     else {
;                         if (opaque_tid(wv) == 0) *qslot = G + (int)atomicAdd(ctr, 1u);
;                         __syncthreads();
;                         idx = *qslot;
;                         __syncthreads();
;                     }
;                 } else {
;                     idx = (ui_ == 1) ? (511 - bx) : (ui_ * 256 + bx);
;                     if (ui_ >= 3 || G != 256) idx = 768;
;                 }
;                 if (idx >= 768) break;
;                 const int code = att_code(idx >> 5), bh = idx & 31, type = code >> 3, qb = code & 7, bb = bh >> 3, h = bh & 7;
;                 if (type == 0) attn_unit<0>(bb, h, qb, (const bf16_t*)(ws + WS_QM), (const bf16_t*)(ws + WS_KN), (const bf16_t*)(ws + WS_KR), (const bf16_t*)(ws + WS_VTM), nullptr, gout, (bf16_t*)(ws + WS_OB), lds, wv);
;                 else if (type == 1) attn_unit<1>(bb, h, qb, QK4, QK4 + QS, nullptr, (const bf16_t*)(ws + WS_VTS), nullptr, gout, (bf16_t*)(ws + WS_OB), lds, wv);
;                 else attn_unit<2>(bb, h, qb, QK4 + 2 * QS, QK4 + 3 * QS, nullptr, (const bf16_t*)(ws + WS_VTS) + (size_t)512 * MTOK, (const float*)(ws + WS_NF2), gout, (bf16_t*)(ws + WS_OB), lds, wv);
.LBB0_530:
	s_cmpk_gt_i32 s1, 0x2ff
	s_mov_b64 s[2:3], -1
	s_cbranch_scc1 .LBB0_523
	s_ashr_i32 s0, s1, 5
	s_add_i32 s4, s0, -12
	s_cmp_lt_i32 s0, 12
	s_mov_b32 s2, 0x214c742
	s_cselect_b32 s3, s2, 0x802320c
	s_mov_b32 s2, 0x54b635cf
	s_cselect_b32 s0, s0, s4
	s_cselect_b32 s2, s2, 0xe82ad877
	s_mul_i32 s0, s0, 5
	s_lshr_b64 s[2:3], s[2:3], s0
	v_writelane_b32 v254, s8, 59
	s_and_b32 s3, s2, 24
	s_and_b32 s0, s2, 7
	s_bfe_u32 s95, s1, 0x20003
	s_and_b32 s33, s1, 7
	s_lshl_b32 s4, s95, 3
	s_add_i32 s4, s4, s0
	v_writelane_b32 v255, s4, 8
	s_mov_b64 s[6:7], -1
	v_writelane_b32 v254, s3, 60
	s_cmp_eq_u32 s3, 8
	s_cbranch_scc1 .Lsw_skip
	s_cmp_eq_u32 s100, 0
	s_cbranch_scc1 .Lsw_skip
	v_readlane_b32 s2, v255, 11
	v_readlane_b32 s4, v254, 57
	s_add_u32 s4, s4, 1
	s_cmp_eq_u32 s2, s4
	s_cbranch_scc1 .Lsw_skip
	v_writelane_b32 v255, s4, 11
	s_cmp_lg_u32 s94, 0
	s_cbranch_scc1 .Lsw_join
	s_lshl_b32 s2, s4, 3
	v_readlane_b32 s4, v251, 45
	v_readlane_b32 s5, v251, 46
	s_add_u32 s4, s4, 0x6c00
	s_addc_u32 s5, s5, 0
	s_mov_b64 exec, 1
	v_mov_b32_e32 v2, 0
	v_mov_b32_e32 v4, 0
.Lsw_poll:
	global_load_dword v3, v2, s[4:5] sc1
	s_waitcnt vmcnt(0)
	v_cmp_le_u32_e32 vcc, s2, v3
	s_cbranch_vccnz .Lsw_done
	s_sleep 1
	v_add_u32_e32 v4, 1, v4
	v_cmp_gt_u32_e32 vcc, 0x400000, v4
	s_cbranch_vccnz .Lsw_poll
.Lsw_done:
	s_mov_b64 exec, -1
.Lsw_join:
	s_barrier
.Lsw_skip:
	s_cmp_lt_i32 s3, 8
	s_mov_b64 s[4:5], 0
	s_cbranch_scc0 .LBB0_535
	s_and_b64 vcc, exec, s[6:7]
	s_mov_b64 s[2:3], 0
	s_cbranch_vccnz .LBB0_649

; #define LAS __attribute__((address_space(3)))
; __device__ __forceinline__ unsigned xb_ld(unsigned* p)              { return __hip_atomic_load(p, __ATOMIC_RELAXED, __HIP_MEMORY_SCOPE_AGENT); }
; __device__ __forceinline__ unsigned xb_add(unsigned* p, unsigned v) { return __hip_atomic_fetch_add(p, v, __ATOMIC_RELAXED, __HIP_MEMORY_SCOPE_AGENT); }
; __device__ __forceinline__ unsigned xb_xcc_id() { return (unsigned)__builtin_amdgcn_s_getreg((3 << 11) | 20) & 0xFu; }
; #define XB_SPIN(cond, bar) do { unsigned _sp = 0; while (cond) { __builtin_amdgcn_s_sleep(1); \
;     if ((++_sp & 255u) == 0u) { if (xb_ld(&(bar)[XB_TMO])) break; if (_sp > XB_SPIN_CAP) { atomicAdd(&(bar)[XB_TMO], 1u); break; } } } } while (0)
; __device__ __forceinline__ void xcd_barrier(unsigned* bar, volatile LAS unsigned* st, bool is0) {
;     asm volatile("s_waitcnt vmcnt(0)" ::: "memory");
;     __syncthreads();
;     if (is0) {
;         __builtin_amdgcn_s_waitcnt(0);
;         const unsigned x = xb_xcc_id();
;         unsigned nloc = st[0], nx = st[1];
;         if (nloc == 0u) { xcd_barrier_complete(bar, x, nloc, nx); st[0] = nloc; st[1] = nx; }
;         const unsigned old = xb_add(&bar[XB_XSUB(x)], 1u);
;         const unsigned gen = old / nloc;
;         if (old + 1u == (gen + 1u) * nloc) {
;             __builtin_amdgcn_fence(__ATOMIC_RELEASE, "agent");
;             asm volatile("s_waitcnt vmcnt(0)" ::: "memory");
;             const unsigned og = xb_add(&bar[XB_TOP], 1u);
;             const unsigned tg = og / nx;
;             if (og + 1u == (tg + 1u) * nx) xb_add(&bar[XB_TOPGEN], 1u);
;             else XB_SPIN(xb_ld(&bar[XB_TOPGEN]) == tg, bar);
;             __builtin_amdgcn_fence(__ATOMIC_ACQUIRE, "agent");
;             xb_add(&bar[XB_XGEN(x)], 1u);
;             asm volatile("s_waitcnt vmcnt(0)" ::: "memory");
;         } else {
;             XB_SPIN(xb_ld(&bar[XB_XGEN(x)]) == gen, bar);
;             __builtin_amdgcn_fence(__ATOMIC_ACQUIRE, "agent");
;             asm volatile("s_waitcnt vmcnt(0)" ::: "memory");
;         }
;     }
;     __syncthreads();
; }
.Lgb_help_3:
	s_branch .Lgb_join_3
